# k17 plus prologue balance: x rows 7/19 per wave (S5-building workgroups / others), bf16(p) loop skipped on the S5-building workgroups, weight-transpose items in reverse wave order
# speedup vs baseline: 1.0092x; 1.0025x over previous
; __device__ __forceinline__ unsigned cvt_pk_bf16(float lo, float hi) { unsigned r; asm volatile("v_cvt_pk_bf16_f32 %0, %1, %2" : "=v"(r) : "v"(lo), "v"(hi)); return r; }
; #define GAS __attribute__((address_space(1)))
; __device__ __forceinline__ float wave_sum(float v) {
; #pragma unroll
;     for (int o = 1; o < 64; o <<= 1) v += __shfl_xor(v, o);
;     return v;
; }
; __device__ __forceinline__ void p0_prologue(const In& in, float* out, unsigned char* ws, LAS unsigned char* lds, int tid, int lane, int wave) {
;     ...
;     { bf16* XB = (bf16*)(ws + WS_XB); float* ss1 = (float*)(ws + WS_STAT) + ST_SS1 * MROWS;
;       for (int mm = gw; mm < MROWS * P0_REP; mm += NGW) { const int m = mm % MROWS; const GAS f32x4* xr = (const GAS f32x4*)(in.x + (size_t)m * DM) + lane; GAS v2u* o = (GAS v2u*)(XB + (size_t)m * DM) + lane; float s = 0.f;
; #pragma unroll
;           for (int j = 0; j < 8; ++j) { const f32x4 v = xr[64 * j]; s += (v.x * v.x + v.y * v.y) + (v.z * v.z + v.w * v.w); v2u w; w.x = cvt_pk_bf16(v.x, v.y); w.y = cvt_pk_bf16(v.z, v.w); o[64 * j] = w; }
;           s = wave_sum(s); if (lane == 0) ss1[m] = s; } }
.Lxb_entry:
	s_mov_b64 s[0:1], exec
	v_lshlrev_b32_e32 v2, 4, v74
	v_lshlrev_b32_e32 v3, 3, v74
	v_mov_b32_e32 v4, 0
	v_mbcnt_hi_u32_b32 v5, -1, v254
	v_xor_b32_e32 v68, 1, v5
	v_xor_b32_e32 v69, 2, v5
	v_xor_b32_e32 v70, 4, v5
	v_xor_b32_e32 v71, 8, v5
	v_xor_b32_e32 v72, 16, v5
	v_xor_b32_e32 v73, 32, v5
	v_lshlrev_b32_e32 v68, 2, v68
	v_lshlrev_b32_e32 v69, 2, v69
	v_lshlrev_b32_e32 v70, 2, v70
	v_lshlrev_b32_e32 v71, 2, v71
	v_lshlrev_b32_e32 v72, 2, v72
	v_lshlrev_b32_e32 v73, 2, v73
	s_mov_b32 s6, s24
	s_mov_b32 s7, s26
	s_movk_i32 s10, 0x7fff
	s_cmpk_lg_u32 s70, 0x100
	s_cbranch_scc1 .Lxb_norm
	s_cmpk_lt_u32 s2, 64
	s_cbranch_scc0 .Lxb_big
	s_movk_i32 s7, 0x200
	s_movk_i32 s10, 0xdff
	s_branch .Lxb_norm
.Lxb_big:
	s_add_i32 s6, s24, 0xc00
	s_movk_i32 s7, 0x600
